# prep_dn conv-weight staging through direct HBM-to-LDS loads (global_load_lds_dword, m0 per group of four) instead of VGPR staging plus ds_write
# baseline (speedup 1.0000x reference)
; DI void prep_dn(const Params& p, int layer, int tile, char* lds) {
;     ...
;   __syncthreads();
;   for (int e = tid; e < 3840; e += 256) cw[e] = p.dn_conv_w[(size_t)layer * 3840 + e];
;   __syncthreads();
.LBB0_275:
	s_andn2_b64 vcc, exec, s[0:1]
	s_cbranch_vccnz .LBB0_340
	s_waitcnt vmcnt(7)
	v_mov_b32_e32 v102, v248
	s_movk_i32 s0, 0xf00
	s_nop 0
	v_cmp_gt_i32_e32 vcc, s0, v102
	s_barrier
	s_and_saveexec_b64 s[0:1], vcc
	s_cbranch_execz .LBB0_284
	v_lshlrev_b32_e32 v2, 2, v102
	v_mov_b32_e32 v3, 0
	v_lshl_add_u64 v[2:3], s[6:7], 0, v[2:3]
	v_readfirstlane_b32 s2, v102
	s_mov_b64 s[8:9], 0x1000
	s_lshl_b32 s2, s2, 2
	s_add_i32 s2, s2, s88
	s_mov_b32 m0, s2
	s_nop 0
	global_load_lds_dword v[2:3], off
	global_load_lds_dword v[2:3], off offset:1024
	global_load_lds_dword v[2:3], off offset:2048
	global_load_lds_dword v[2:3], off offset:3072
	s_addk_i32 s2, 0x1000
	v_lshl_add_u64 v[2:3], v[2:3], 0, s[8:9]
	s_mov_b32 m0, s2
	s_nop 0
	global_load_lds_dword v[2:3], off
	global_load_lds_dword v[2:3], off offset:1024
	global_load_lds_dword v[2:3], off offset:2048
	global_load_lds_dword v[2:3], off offset:3072
	s_addk_i32 s2, 0x1000
	v_lshl_add_u64 v[2:3], v[2:3], 0, s[8:9]
	s_mov_b32 m0, s2
	s_nop 0
	global_load_lds_dword v[2:3], off
	global_load_lds_dword v[2:3], off offset:1024
	global_load_lds_dword v[2:3], off offset:2048
	global_load_lds_dword v[2:3], off offset:3072
	s_addk_i32 s2, 0x1000
	v_lshl_add_u64 v[2:3], v[2:3], 0, s[8:9]
	s_mov_b32 m0, s2
	s_nop 0
	global_load_lds_dword v[2:3], off
	global_load_lds_dword v[2:3], off offset:1024
	global_load_lds_dword v[2:3], off offset:2048
	s_waitcnt vmcnt(0)
